# same as previous plus 14 s_nop padding so downstream code keeps its 64-byte alignment phase
# speedup vs baseline: 1.0123x; 1.0123x over previous
.LBB0_20:
	v_writelane_b32 v253, s68, 40
	s_lshl_b32 s0, s80, 9
	v_add_u32_e32 v10, s0, v8
	v_writelane_b32 v253, s69, 41
	v_writelane_b32 v253, s70, 42
	v_writelane_b32 v253, s71, 43
	v_writelane_b32 v253, s72, 44
	v_writelane_b32 v253, s73, 45
	v_writelane_b32 v253, s74, 46
	v_writelane_b32 v253, s75, 47
	v_writelane_b32 v253, s0, 48
	s_lshl_b32 s92, s96, 9
	s_mov_b64 s[2:3], exec
	v_readlane_b32 s8, v253, 20
	v_readlane_b32 s9, v253, 21
	v_readlane_b32 s10, v253, 30
	v_readlane_b32 s11, v253, 31
	v_readlane_b32 s12, v253, 28
	v_readlane_b32 s13, v253, 29
	v_readlane_b32 s14, v253, 34
	v_readlane_b32 s15, v253, 35
	v_readlane_b32 s16, v253, 32
	v_readlane_b32 s17, v253, 33
	v_readlane_b32 s18, v253, 36
	v_readlane_b32 s19, v253, 37
	v_readlane_b32 s20, v253, 38
	v_readlane_b32 s21, v253, 39
	v_mov_b32_e32 v11, 0
	v_mov_b32_e32 v192, v10
	v_cmp_gt_u32_e32 vcc, 0x6d000, v192
	s_mov_b64 s[36:37], vcc
	s_mov_b32 s1, 0x12c9fc
	v_mul_hi_u32 v193, v192, s1
	v_mul_u32_u24_e32 v194, 0xda0, v193
	v_sub_u32_e32 v194, v192, v194
	v_mul_u32_u24_e32 v195, 0x37400, v193
	v_lshl_add_u32 v195, v194, 2, v195
	v_lshlrev_b32_e32 v196, 11, v194
	v_lshl_add_u32 v196, v193, 4, v196
	v_add_u32_e32 v196, 0x400000, v196
	s_mov_b64 exec, s[36:37]
	global_load_dword v104, v195, s[8:9]
	v_add_u32_e32 v195, 0x6e80, v195
	global_load_dword v105, v195, s[8:9]
	v_add_u32_e32 v195, 0x6e80, v195
	global_load_dword v106, v195, s[8:9]
	v_add_u32_e32 v195, 0x6e80, v195
	global_load_dword v107, v195, s[8:9]
	v_add_u32_e32 v195, 0x6e80, v195
	global_load_dword v108, v195, s[8:9]
	v_add_u32_e32 v195, 0x6e80, v195
	global_load_dword v109, v195, s[8:9]
	v_add_u32_e32 v195, 0x6e80, v195
	global_load_dword v110, v195, s[8:9]
	v_add_u32_e32 v195, 0x6e80, v195
	global_load_dword v111, v195, s[8:9]
	s_mov_b64 exec, s[2:3]
	s_mul_i32 s0, s92, 1
	v_add_u32_e32 v200, s0, v10
	v_cmp_gt_u32_e32 vcc, 0x6d000, v200
	s_mov_b64 s[38:39], vcc
	s_mov_b32 s1, 0x12c9fc
	v_mul_hi_u32 v201, v200, s1
	v_mul_u32_u24_e32 v202, 0xda0, v201
	v_sub_u32_e32 v202, v200, v202
	v_mul_u32_u24_e32 v203, 0x37400, v201
	v_lshl_add_u32 v203, v202, 2, v203
	v_lshlrev_b32_e32 v204, 11, v202
	v_lshl_add_u32 v204, v201, 4, v204
	v_add_u32_e32 v204, 0x400000, v204
	s_mov_b64 exec, s[38:39]
	global_load_dword v120, v203, s[8:9]
	v_add_u32_e32 v203, 0x6e80, v203
	global_load_dword v121, v203, s[8:9]
	v_add_u32_e32 v203, 0x6e80, v203
	global_load_dword v122, v203, s[8:9]
	v_add_u32_e32 v203, 0x6e80, v203
	global_load_dword v123, v203, s[8:9]
	v_add_u32_e32 v203, 0x6e80, v203
	global_load_dword v124, v203, s[8:9]
	v_add_u32_e32 v203, 0x6e80, v203
	global_load_dword v125, v203, s[8:9]
	v_add_u32_e32 v203, 0x6e80, v203
	global_load_dword v126, v203, s[8:9]
	v_add_u32_e32 v203, 0x6e80, v203
	global_load_dword v127, v203, s[8:9]
	s_mov_b64 exec, s[2:3]
	v_mov_b32_e32 v208, v10
	v_cmp_gt_u32_e32 vcc, 0x70000, v208
	s_mov_b64 s[40:41], vcc
	s_mov_b32 s1, 0x124925
	v_mul_hi_u32 v209, v208, s1
	v_mul_u32_u24_e32 v210, 0xe00, v209
	v_sub_u32_e32 v210, v208, v210
	v_mul_u32_u24_e32 v211, 0x37400, v209
	v_lshl_add_u32 v211, v210, 2, v211
	v_add_u32_e32 v211, 0x3680, v211
	v_lshlrev_b32_e32 v212, 11, v210
	v_lshl_add_u32 v212, v209, 4, v212
	v_add_u32_e32 v212, 0xb00000, v212
	s_mov_b64 exec, s[40:41]
	global_load_dword v136, v211, s[8:9]
	v_add_u32_e32 v211, 0x6e80, v211
	global_load_dword v137, v211, s[8:9]
	v_add_u32_e32 v211, 0x6e80, v211
	global_load_dword v138, v211, s[8:9]
	v_add_u32_e32 v211, 0x6e80, v211
	global_load_dword v139, v211, s[8:9]
	v_add_u32_e32 v211, 0x6e80, v211
	global_load_dword v140, v211, s[8:9]
	v_add_u32_e32 v211, 0x6e80, v211
	global_load_dword v141, v211, s[8:9]
	v_add_u32_e32 v211, 0x6e80, v211
	global_load_dword v142, v211, s[8:9]
	v_add_u32_e32 v211, 0x6e80, v211
	global_load_dword v143, v211, s[8:9]
	s_mov_b64 exec, s[2:3]
	s_mul_i32 s0, s92, 1
	v_add_u32_e32 v216, s0, v10
	v_cmp_gt_u32_e32 vcc, 0x70000, v216
	s_mov_b64 s[42:43], vcc
	s_mov_b32 s1, 0x124925
	v_mul_hi_u32 v217, v216, s1
	v_mul_u32_u24_e32 v218, 0xe00, v217
	v_sub_u32_e32 v218, v216, v218
	v_mul_u32_u24_e32 v219, 0x37400, v217
	v_lshl_add_u32 v219, v218, 2, v219
	v_add_u32_e32 v219, 0x3680, v219
	v_lshlrev_b32_e32 v220, 11, v218
	v_lshl_add_u32 v220, v217, 4, v220
	v_add_u32_e32 v220, 0xb00000, v220
	s_mov_b64 exec, s[42:43]
	global_load_dword v152, v219, s[8:9]
	v_add_u32_e32 v219, 0x6e80, v219
	global_load_dword v153, v219, s[8:9]
	v_add_u32_e32 v219, 0x6e80, v219
	global_load_dword v154, v219, s[8:9]
	v_add_u32_e32 v219, 0x6e80, v219
	global_load_dword v155, v219, s[8:9]
	v_add_u32_e32 v219, 0x6e80, v219
	global_load_dword v156, v219, s[8:9]
	v_add_u32_e32 v219, 0x6e80, v219
	global_load_dword v157, v219, s[8:9]
	v_add_u32_e32 v219, 0x6e80, v219
	global_load_dword v158, v219, s[8:9]
	v_add_u32_e32 v219, 0x6e80, v219
	global_load_dword v159, v219, s[8:9]
	s_mov_b64 exec, s[2:3]
	v_mov_b32_e32 v224, v10
	v_cmp_gt_u32_e32 vcc, 0x20000, v224
	s_mov_b64 s[44:45], vcc
	v_lshrrev_b32_e32 v225, 10, v224
	v_and_b32_e32 v226, 0x3ff, v224
	v_mul_u32_u24_e32 v227, 0x8000, v225
	v_lshl_add_u32 v227, v226, 2, v227
	v_lshlrev_b32_e32 v228, 11, v226
	v_lshl_add_u32 v228, v225, 4, v228
	v_add_u32_e32 v228, 0x1700000, v228
	s_mov_b64 exec, s[44:45]
	global_load_dword v176, v227, s[70:71]
	v_add_u32_e32 v227, 0x1000, v227
	global_load_dword v177, v227, s[70:71]
	v_add_u32_e32 v227, 0x1000, v227
	global_load_dword v178, v227, s[70:71]
	v_add_u32_e32 v227, 0x1000, v227
	global_load_dword v179, v227, s[70:71]
	v_add_u32_e32 v227, 0x1000, v227
	global_load_dword v180, v227, s[70:71]
	v_add_u32_e32 v227, 0x1000, v227
	global_load_dword v181, v227, s[70:71]
	v_add_u32_e32 v227, 0x1000, v227
	global_load_dword v182, v227, s[70:71]
	v_add_u32_e32 v227, 0x1000, v227
	global_load_dword v183, v227, s[70:71]
	s_mov_b64 exec, s[2:3]
	s_waitcnt vmcnt(0)
	s_mov_b64 exec, s[36:37]
	v_cvt_pk_bf16_f32 v104, v104, v105
	v_cvt_pk_bf16_f32 v105, v106, v107
	v_cvt_pk_bf16_f32 v106, v108, v109
	v_cvt_pk_bf16_f32 v107, v110, v111
	global_store_dwordx4 v196, v[104:107], s[94:95]
	s_mov_b64 exec, s[2:3]
	s_mov_b64 exec, s[38:39]
	v_cvt_pk_bf16_f32 v120, v120, v121
	v_cvt_pk_bf16_f32 v121, v122, v123
	v_cvt_pk_bf16_f32 v122, v124, v125
	v_cvt_pk_bf16_f32 v123, v126, v127
	global_store_dwordx4 v204, v[120:123], s[94:95]
	s_mov_b64 exec, s[2:3]
	s_mov_b64 exec, s[40:41]
	v_cvt_pk_bf16_f32 v136, v136, v137
	v_cvt_pk_bf16_f32 v137, v138, v139
	v_cvt_pk_bf16_f32 v138, v140, v141
	v_cvt_pk_bf16_f32 v139, v142, v143
	global_store_dwordx4 v212, v[136:139], s[94:95]
	s_mov_b64 exec, s[2:3]
	s_mov_b64 exec, s[42:43]
	v_cvt_pk_bf16_f32 v152, v152, v153
	v_cvt_pk_bf16_f32 v153, v154, v155
	v_cvt_pk_bf16_f32 v154, v156, v157
	v_cvt_pk_bf16_f32 v155, v158, v159
	global_store_dwordx4 v220, v[152:155], s[94:95]
	s_mov_b64 exec, s[2:3]
	s_mov_b64 exec, s[44:45]
	v_cvt_pk_bf16_f32 v176, v176, v177
	v_cvt_pk_bf16_f32 v177, v178, v179
	v_cvt_pk_bf16_f32 v178, v180, v181
	v_cvt_pk_bf16_f32 v179, v182, v183
	global_store_dwordx4 v228, v[176:179], s[94:95]
	s_mov_b64 exec, s[2:3]
	s_mul_i32 s0, s92, 2
	v_add_u32_e32 v192, s0, v10
	v_cmp_gt_u32_e32 vcc, 0x6d000, v192
	s_mov_b64 s[36:37], vcc
	s_mov_b32 s1, 0x12c9fc
	v_mul_hi_u32 v193, v192, s1
	v_mul_u32_u24_e32 v194, 0xda0, v193
	v_sub_u32_e32 v194, v192, v194
	v_mul_u32_u24_e32 v195, 0x37400, v193
	v_lshl_add_u32 v195, v194, 2, v195
	v_lshlrev_b32_e32 v196, 11, v194
	v_lshl_add_u32 v196, v193, 4, v196
	v_add_u32_e32 v196, 0x400000, v196
	s_mov_b64 exec, s[36:37]
	global_load_dword v104, v195, s[8:9]
	v_add_u32_e32 v195, 0x6e80, v195
	global_load_dword v105, v195, s[8:9]
	v_add_u32_e32 v195, 0x6e80, v195
	global_load_dword v106, v195, s[8:9]
	v_add_u32_e32 v195, 0x6e80, v195
	global_load_dword v107, v195, s[8:9]
	v_add_u32_e32 v195, 0x6e80, v195
	global_load_dword v108, v195, s[8:9]
	v_add_u32_e32 v195, 0x6e80, v195
	global_load_dword v109, v195, s[8:9]
	v_add_u32_e32 v195, 0x6e80, v195
	global_load_dword v110, v195, s[8:9]
	v_add_u32_e32 v195, 0x6e80, v195
	global_load_dword v111, v195, s[8:9]
	s_mov_b64 exec, s[2:3]
	s_mul_i32 s0, s92, 3
	v_add_u32_e32 v200, s0, v10
	v_cmp_gt_u32_e32 vcc, 0x6d000, v200
	s_mov_b64 s[38:39], vcc
	s_mov_b32 s1, 0x12c9fc
	v_mul_hi_u32 v201, v200, s1
	v_mul_u32_u24_e32 v202, 0xda0, v201
	v_sub_u32_e32 v202, v200, v202
	v_mul_u32_u24_e32 v203, 0x37400, v201
	v_lshl_add_u32 v203, v202, 2, v203
	v_lshlrev_b32_e32 v204, 11, v202
	v_lshl_add_u32 v204, v201, 4, v204
	v_add_u32_e32 v204, 0x400000, v204
	s_mov_b64 exec, s[38:39]
	global_load_dword v120, v203, s[8:9]
	v_add_u32_e32 v203, 0x6e80, v203
	global_load_dword v121, v203, s[8:9]
	v_add_u32_e32 v203, 0x6e80, v203
	global_load_dword v122, v203, s[8:9]
	v_add_u32_e32 v203, 0x6e80, v203
	global_load_dword v123, v203, s[8:9]
	v_add_u32_e32 v203, 0x6e80, v203
	global_load_dword v124, v203, s[8:9]
	v_add_u32_e32 v203, 0x6e80, v203
	global_load_dword v125, v203, s[8:9]
	v_add_u32_e32 v203, 0x6e80, v203
	global_load_dword v126, v203, s[8:9]
	v_add_u32_e32 v203, 0x6e80, v203
	global_load_dword v127, v203, s[8:9]
	s_mov_b64 exec, s[2:3]
	s_mul_i32 s0, s92, 2
	v_add_u32_e32 v208, s0, v10
	v_cmp_gt_u32_e32 vcc, 0x70000, v208
	s_mov_b64 s[40:41], vcc
	s_mov_b32 s1, 0x124925
	v_mul_hi_u32 v209, v208, s1
	v_mul_u32_u24_e32 v210, 0xe00, v209
	v_sub_u32_e32 v210, v208, v210
	v_mul_u32_u24_e32 v211, 0x37400, v209
	v_lshl_add_u32 v211, v210, 2, v211
	v_add_u32_e32 v211, 0x3680, v211
	v_lshlrev_b32_e32 v212, 11, v210
	v_lshl_add_u32 v212, v209, 4, v212
	v_add_u32_e32 v212, 0xb00000, v212
	s_mov_b64 exec, s[40:41]
	global_load_dword v136, v211, s[8:9]
	v_add_u32_e32 v211, 0x6e80, v211
	global_load_dword v137, v211, s[8:9]
	v_add_u32_e32 v211, 0x6e80, v211
	global_load_dword v138, v211, s[8:9]
	v_add_u32_e32 v211, 0x6e80, v211
	global_load_dword v139, v211, s[8:9]
	v_add_u32_e32 v211, 0x6e80, v211
	global_load_dword v140, v211, s[8:9]
	v_add_u32_e32 v211, 0x6e80, v211
	global_load_dword v141, v211, s[8:9]
	v_add_u32_e32 v211, 0x6e80, v211
	global_load_dword v142, v211, s[8:9]
	v_add_u32_e32 v211, 0x6e80, v211
	global_load_dword v143, v211, s[8:9]
	s_mov_b64 exec, s[2:3]
	s_mul_i32 s0, s92, 3
	v_add_u32_e32 v216, s0, v10
	v_cmp_gt_u32_e32 vcc, 0x70000, v216
	s_mov_b64 s[42:43], vcc
	s_mov_b32 s1, 0x124925
	v_mul_hi_u32 v217, v216, s1
	v_mul_u32_u24_e32 v218, 0xe00, v217
	v_sub_u32_e32 v218, v216, v218
	v_mul_u32_u24_e32 v219, 0x37400, v217
	v_lshl_add_u32 v219, v218, 2, v219
	v_add_u32_e32 v219, 0x3680, v219
	v_lshlrev_b32_e32 v220, 11, v218
	v_lshl_add_u32 v220, v217, 4, v220
	v_add_u32_e32 v220, 0xb00000, v220
	s_mov_b64 exec, s[42:43]
	global_load_dword v152, v219, s[8:9]
	v_add_u32_e32 v219, 0x6e80, v219
	global_load_dword v153, v219, s[8:9]
	v_add_u32_e32 v219, 0x6e80, v219
	global_load_dword v154, v219, s[8:9]
	v_add_u32_e32 v219, 0x6e80, v219
	global_load_dword v155, v219, s[8:9]
	v_add_u32_e32 v219, 0x6e80, v219
	global_load_dword v156, v219, s[8:9]
	v_add_u32_e32 v219, 0x6e80, v219
	global_load_dword v157, v219, s[8:9]
	v_add_u32_e32 v219, 0x6e80, v219
	global_load_dword v158, v219, s[8:9]
	v_add_u32_e32 v219, 0x6e80, v219
	global_load_dword v159, v219, s[8:9]
	s_mov_b64 exec, s[2:3]
	v_mov_b32_e32 v224, v10
	v_cmp_gt_u32_e32 vcc, 0x8000, v224
	s_mov_b64 s[44:45], vcc
	v_lshrrev_b32_e32 v225, 9, v224
	v_and_b32_e32 v226, 0x1ff, v224
	v_mul_u32_u24_e32 v227, 0x4000, v225
	v_lshl_add_u32 v227, v226, 2, v227
	v_lshlrev_b32_e32 v228, 10, v226
	v_lshl_add_u32 v228, v225, 4, v228
	v_add_u32_e32 v228, 0x1300000, v228
	s_mov_b64 exec, s[44:45]
	global_load_dword v176, v227, s[66:67]
	v_add_u32_e32 v227, 0x800, v227
	global_load_dword v177, v227, s[66:67]
	v_add_u32_e32 v227, 0x800, v227
	global_load_dword v178, v227, s[66:67]
	v_add_u32_e32 v227, 0x800, v227
	global_load_dword v179, v227, s[66:67]
	v_add_u32_e32 v227, 0x800, v227
	global_load_dword v180, v227, s[66:67]
	v_add_u32_e32 v227, 0x800, v227
	global_load_dword v181, v227, s[66:67]
	v_add_u32_e32 v227, 0x800, v227
	global_load_dword v182, v227, s[66:67]
	v_add_u32_e32 v227, 0x800, v227
	global_load_dword v183, v227, s[66:67]
	s_mov_b64 exec, s[2:3]
	s_waitcnt vmcnt(0)
	s_mov_b64 exec, s[36:37]
	v_cvt_pk_bf16_f32 v104, v104, v105
	v_cvt_pk_bf16_f32 v105, v106, v107
	v_cvt_pk_bf16_f32 v106, v108, v109
	v_cvt_pk_bf16_f32 v107, v110, v111
	global_store_dwordx4 v196, v[104:107], s[94:95]
	s_mov_b64 exec, s[2:3]
	s_mov_b64 exec, s[38:39]
	v_cvt_pk_bf16_f32 v120, v120, v121
	v_cvt_pk_bf16_f32 v121, v122, v123
	v_cvt_pk_bf16_f32 v122, v124, v125
	v_cvt_pk_bf16_f32 v123, v126, v127
	global_store_dwordx4 v204, v[120:123], s[94:95]
	s_mov_b64 exec, s[2:3]
	s_mov_b64 exec, s[40:41]
	v_cvt_pk_bf16_f32 v136, v136, v137
	v_cvt_pk_bf16_f32 v137, v138, v139
	v_cvt_pk_bf16_f32 v138, v140, v141
	v_cvt_pk_bf16_f32 v139, v142, v143
	global_store_dwordx4 v212, v[136:139], s[94:95]
	s_mov_b64 exec, s[2:3]
	s_mov_b64 exec, s[42:43]
	v_cvt_pk_bf16_f32 v152, v152, v153
	v_cvt_pk_bf16_f32 v153, v154, v155
	v_cvt_pk_bf16_f32 v154, v156, v157
	v_cvt_pk_bf16_f32 v155, v158, v159
	global_store_dwordx4 v220, v[152:155], s[94:95]
	s_mov_b64 exec, s[2:3]
	s_mov_b64 exec, s[44:45]
	v_cvt_pk_bf16_f32 v176, v176, v177
	v_cvt_pk_bf16_f32 v177, v178, v179
	v_cvt_pk_bf16_f32 v178, v180, v181
	v_cvt_pk_bf16_f32 v179, v182, v183
	global_store_dwordx4 v228, v[176:179], s[94:95]
	s_mov_b64 exec, s[2:3]
	v_mov_b32_e32 v192, v10
	v_cmp_gt_u32_e32 vcc, 0x6000, v192
	s_mov_b64 s[36:37], vcc
	s_mov_b32 s1, 0x555556
	v_mul_hi_u32 v193, v192, s1
	v_mul_u32_u24_e32 v194, 0x300, v193
	v_sub_u32_e32 v194, v192, v194
	v_mul_u32_u24_e32 v195, 0x6000, v193
	v_lshl_add_u32 v195, v194, 2, v195
	v_lshlrev_b32_e32 v196, 9, v194
	v_lshl_add_u32 v196, v193, 4, v196
	v_add_u32_e32 v196, 0x1200000, v196
	v_lshlrev_b32_e32 v197, 5, v193
	s_mov_b64 exec, s[36:37]
	global_load_dword v104, v195, s[10:11]
	v_add_u32_e32 v195, 0xc00, v195
	global_load_dword v105, v195, s[10:11]
	v_add_u32_e32 v195, 0xc00, v195
	global_load_dword v106, v195, s[10:11]
	v_add_u32_e32 v195, 0xc00, v195
	global_load_dword v107, v195, s[10:11]
	v_add_u32_e32 v195, 0xc00, v195
	global_load_dword v108, v195, s[10:11]
	v_add_u32_e32 v195, 0xc00, v195
	global_load_dword v109, v195, s[10:11]
	v_add_u32_e32 v195, 0xc00, v195
	global_load_dword v110, v195, s[10:11]
	v_add_u32_e32 v195, 0xc00, v195
	global_load_dword v111, v195, s[10:11]
	global_load_dwordx4 v[112:115], v197, s[12:13]
	global_load_dwordx4 v[116:119], v197, s[12:13] offset:16
	s_mov_b64 exec, s[2:3]
	v_mov_b32_e32 v200, v10
	v_cmp_gt_u32_e32 vcc, 0x4000, v200
	s_mov_b64 s[38:39], vcc
	v_lshrrev_b32_e32 v201, 10, v200
	v_and_b32_e32 v202, 0x3ff, v200
	v_mul_u32_u24_e32 v203, 0x8000, v201
	v_lshl_add_u32 v203, v202, 2, v203
	v_lshlrev_b32_e32 v204, 8, v202
	v_lshl_add_u32 v204, v201, 4, v204
	v_add_u32_e32 v204, 0x1280000, v204
	v_lshlrev_b32_e32 v205, 5, v201
	s_mov_b64 exec, s[38:39]
	global_load_dword v120, v203, s[14:15]
	v_add_u32_e32 v203, 0x1000, v203
	global_load_dword v121, v203, s[14:15]
	v_add_u32_e32 v203, 0x1000, v203
	global_load_dword v122, v203, s[14:15]
	v_add_u32_e32 v203, 0x1000, v203
	global_load_dword v123, v203, s[14:15]
	v_add_u32_e32 v203, 0x1000, v203
	global_load_dword v124, v203, s[14:15]
	v_add_u32_e32 v203, 0x1000, v203
	global_load_dword v125, v203, s[14:15]
	v_add_u32_e32 v203, 0x1000, v203
	global_load_dword v126, v203, s[14:15]
	v_add_u32_e32 v203, 0x1000, v203
	global_load_dword v127, v203, s[14:15]
	global_load_dwordx4 v[128:131], v205, s[16:17]
	global_load_dwordx4 v[132:135], v205, s[16:17] offset:16
	s_mov_b64 exec, s[2:3]
	v_mov_b32_e32 v208, v10
	v_cmp_gt_u32_e32 vcc, 0x10000, v208
	s_mov_b64 s[40:41], vcc
	v_lshrrev_b32_e32 v209, 10, v208
	v_and_b32_e32 v210, 0x3ff, v208
	v_mul_u32_u24_e32 v211, 0x8000, v209
	v_lshl_add_u32 v211, v210, 2, v211
	v_lshlrev_b32_e32 v212, 10, v210
	v_lshl_add_u32 v212, v209, 4, v212
	v_add_u32_e32 v212, 0x1400000, v212
	s_mov_b64 exec, s[40:41]
	global_load_dword v136, v211, s[18:19]
	v_add_u32_e32 v211, 0x1000, v211
	global_load_dword v137, v211, s[18:19]
	v_add_u32_e32 v211, 0x1000, v211
	global_load_dword v138, v211, s[18:19]
	v_add_u32_e32 v211, 0x1000, v211
	global_load_dword v139, v211, s[18:19]
	v_add_u32_e32 v211, 0x1000, v211
	global_load_dword v140, v211, s[18:19]
	v_add_u32_e32 v211, 0x1000, v211
	global_load_dword v141, v211, s[18:19]
	v_add_u32_e32 v211, 0x1000, v211
	global_load_dword v142, v211, s[18:19]
	v_add_u32_e32 v211, 0x1000, v211
	global_load_dword v143, v211, s[18:19]
	s_mov_b64 exec, s[2:3]
	v_mov_b32_e32 v216, v10
	v_cmp_gt_u32_e32 vcc, 0x10000, v216
	s_mov_b64 s[42:43], vcc
	v_lshrrev_b32_e32 v217, 10, v216
	v_and_b32_e32 v218, 0x3ff, v216
	v_mul_u32_u24_e32 v219, 0x8000, v217
	v_lshl_add_u32 v219, v218, 2, v219
	v_lshlrev_b32_e32 v220, 10, v218
	v_lshl_add_u32 v220, v217, 4, v220
	v_add_u32_e32 v220, 0x1500000, v220
	s_mov_b64 exec, s[42:43]
	global_load_dword v152, v219, s[20:21]
	v_add_u32_e32 v219, 0x1000, v219
	global_load_dword v153, v219, s[20:21]
	v_add_u32_e32 v219, 0x1000, v219
	global_load_dword v154, v219, s[20:21]
	v_add_u32_e32 v219, 0x1000, v219
	global_load_dword v155, v219, s[20:21]
	v_add_u32_e32 v219, 0x1000, v219
	global_load_dword v156, v219, s[20:21]
	v_add_u32_e32 v219, 0x1000, v219
	global_load_dword v157, v219, s[20:21]
	v_add_u32_e32 v219, 0x1000, v219
	global_load_dword v158, v219, s[20:21]
	v_add_u32_e32 v219, 0x1000, v219
	global_load_dword v159, v219, s[20:21]
	s_mov_b64 exec, s[2:3]
	v_mov_b32_e32 v224, v10
	v_cmp_gt_u32_e32 vcc, 0x10000, v224
	s_mov_b64 s[44:45], vcc
	v_lshrrev_b32_e32 v225, 10, v224
	v_and_b32_e32 v226, 0x3ff, v224
	v_mul_u32_u24_e32 v227, 0x8000, v225
	v_lshl_add_u32 v227, v226, 2, v227
	v_lshlrev_b32_e32 v228, 10, v226
	v_lshl_add_u32 v228, v225, 4, v228
	v_add_u32_e32 v228, 0x1600000, v228
	s_mov_b64 exec, s[44:45]
	global_load_dword v176, v227, s[68:69]
	v_add_u32_e32 v227, 0x1000, v227
	global_load_dword v177, v227, s[68:69]
	v_add_u32_e32 v227, 0x1000, v227
	global_load_dword v178, v227, s[68:69]
	v_add_u32_e32 v227, 0x1000, v227
	global_load_dword v179, v227, s[68:69]
	v_add_u32_e32 v227, 0x1000, v227
	global_load_dword v180, v227, s[68:69]
	v_add_u32_e32 v227, 0x1000, v227
	global_load_dword v181, v227, s[68:69]
	v_add_u32_e32 v227, 0x1000, v227
	global_load_dword v182, v227, s[68:69]
	v_add_u32_e32 v227, 0x1000, v227
	global_load_dword v183, v227, s[68:69]
	s_mov_b64 exec, s[2:3]
	s_waitcnt vmcnt(0)
	s_mov_b64 exec, s[36:37]
	v_mul_f32_e32 v104, v104, v112
	v_mul_f32_e32 v105, v105, v113
	v_mul_f32_e32 v106, v106, v114
	v_mul_f32_e32 v107, v107, v115
	v_mul_f32_e32 v108, v108, v116
	v_mul_f32_e32 v109, v109, v117
	v_mul_f32_e32 v110, v110, v118
	v_mul_f32_e32 v111, v111, v119
	v_cvt_pk_bf16_f32 v104, v104, v105
	v_cvt_pk_bf16_f32 v105, v106, v107
	v_cvt_pk_bf16_f32 v106, v108, v109
	v_cvt_pk_bf16_f32 v107, v110, v111
	global_store_dwordx4 v196, v[104:107], s[94:95]
	s_mov_b64 exec, s[2:3]
	s_mov_b64 exec, s[38:39]
	v_mul_f32_e32 v120, v120, v128
	v_mul_f32_e32 v121, v121, v129
	v_mul_f32_e32 v122, v122, v130
	v_mul_f32_e32 v123, v123, v131
	v_mul_f32_e32 v124, v124, v132
	v_mul_f32_e32 v125, v125, v133
	v_mul_f32_e32 v126, v126, v134
	v_mul_f32_e32 v127, v127, v135
	v_cvt_pk_bf16_f32 v120, v120, v121
	v_cvt_pk_bf16_f32 v121, v122, v123
	v_cvt_pk_bf16_f32 v122, v124, v125
	v_cvt_pk_bf16_f32 v123, v126, v127
	global_store_dwordx4 v204, v[120:123], s[94:95]
	s_mov_b64 exec, s[2:3]
	s_mov_b64 exec, s[40:41]
	v_cvt_pk_bf16_f32 v136, v136, v137
	v_cvt_pk_bf16_f32 v137, v138, v139
	v_cvt_pk_bf16_f32 v138, v140, v141
	v_cvt_pk_bf16_f32 v139, v142, v143
	global_store_dwordx4 v212, v[136:139], s[94:95]
	s_mov_b64 exec, s[2:3]
	s_mov_b64 exec, s[42:43]
	v_cvt_pk_bf16_f32 v152, v152, v153
	v_cvt_pk_bf16_f32 v153, v154, v155
	v_cvt_pk_bf16_f32 v154, v156, v157
	v_cvt_pk_bf16_f32 v155, v158, v159
	global_store_dwordx4 v220, v[152:155], s[94:95]
	s_mov_b64 exec, s[2:3]
	s_mov_b64 exec, s[44:45]
	v_cvt_pk_bf16_f32 v176, v176, v177
	v_cvt_pk_bf16_f32 v177, v178, v179
	v_cvt_pk_bf16_f32 v178, v180, v181
	v_cvt_pk_bf16_f32 v179, v182, v183
	global_store_dwordx4 v228, v[176:179], s[94:95]
	s_mov_b64 exec, s[2:3]
	v_cmp_gt_u32_e32 vcc, 0x3000, v10
	v_lshlrev_b32_e32 v192, 4, v10
	v_add_u32_e32 v192, 0xad0000, v192
	v_mov_b32_e32 v104, 0
	v_mov_b32_e32 v105, 0
	v_mov_b32_e32 v106, 0
	v_mov_b32_e32 v107, 0
	s_and_b64 exec, s[2:3], vcc
	global_store_dwordx4 v192, v[104:107], s[94:95]
	s_mov_b64 exec, s[2:3]
	s_nop 0
	s_nop 0
	s_nop 0
	s_nop 0
	s_nop 0
	s_nop 0
	s_nop 0
	s_nop 0
	s_nop 0
	s_nop 0
	s_nop 0
	s_nop 0
	s_nop 0
	s_nop 0
